# baseline (speedup 1.0000x reference)
.LBB0_902:
	s_or_b64 exec, exec, s[0:1]
	v_cmp_lt_i32_e32 vcc, -1, v118
	s_and_saveexec_b64 s[0:1], vcc
	s_cbranch_execz .LBB0_897
	v_mov_b32_e32 v119, v1
	v_lshlrev_b64 v[226:227], 11, v[118:119]
	v_pk_mul_f32 v[18:19], v[114:115], v[18:19] op_sel_hi:[0,1]
	v_pk_mul_f32 v[20:21], v[114:115], v[20:21] op_sel_hi:[0,1]
	v_pk_mul_f32 v[22:23], v[114:115], v[22:23] op_sel_hi:[0,1]
	v_pk_mul_f32 v[24:25], v[114:115], v[24:25] op_sel_hi:[0,1]
	v_pk_mul_f32 v[26:27], v[114:115], v[26:27] op_sel_hi:[0,1]
	v_pk_mul_f32 v[28:29], v[114:115], v[28:29] op_sel_hi:[0,1]
	v_pk_mul_f32 v[30:31], v[114:115], v[30:31] op_sel_hi:[0,1]
	v_pk_mul_f32 v[32:33], v[114:115], v[32:33] op_sel_hi:[0,1]
	v_pk_mul_f32 v[2:3], v[114:115], v[2:3] op_sel_hi:[0,1]
	v_pk_mul_f32 v[4:5], v[114:115], v[4:5] op_sel_hi:[0,1]
	v_pk_mul_f32 v[6:7], v[114:115], v[6:7] op_sel_hi:[0,1]
	v_pk_mul_f32 v[8:9], v[114:115], v[8:9] op_sel_hi:[0,1]
	v_pk_mul_f32 v[10:11], v[114:115], v[10:11] op_sel_hi:[0,1]
	v_pk_mul_f32 v[12:13], v[114:115], v[12:13] op_sel_hi:[0,1]
	v_pk_mul_f32 v[14:15], v[114:115], v[14:15] op_sel_hi:[0,1]
	v_pk_mul_f32 v[16:17], v[114:115], v[16:17] op_sel_hi:[0,1]
	v_lshl_add_u64 v[226:227], v[66:67], 0, v[226:227]
	v_lshl_add_u64 v[226:227], v[0:1], 0, v[226:227]
	v_cvt_pk_bf16_f32 v210, v18, v19
	v_cvt_pk_bf16_f32 v211, v20, v21
	v_cvt_pk_bf16_f32 v212, v22, v23
	v_cvt_pk_bf16_f32 v213, v24, v25
	v_cvt_pk_bf16_f32 v214, v26, v27
	v_cvt_pk_bf16_f32 v215, v28, v29
	v_cvt_pk_bf16_f32 v216, v30, v31
	v_cvt_pk_bf16_f32 v217, v32, v33
	v_cvt_pk_bf16_f32 v218, v2, v3
	v_cvt_pk_bf16_f32 v219, v4, v5
	v_cvt_pk_bf16_f32 v220, v6, v7
	v_cvt_pk_bf16_f32 v221, v8, v9
	v_cvt_pk_bf16_f32 v222, v10, v11
	v_cvt_pk_bf16_f32 v223, v12, v13
	v_cvt_pk_bf16_f32 v224, v14, v15
	v_cvt_pk_bf16_f32 v225, v16, v17
	s_nop 1
	v_permlane32_swap_b32_e32 v210, v212
	v_permlane32_swap_b32_e32 v211, v213
	v_permlane32_swap_b32_e32 v214, v216
	v_permlane32_swap_b32_e32 v215, v217
	v_permlane32_swap_b32_e32 v218, v220
	v_permlane32_swap_b32_e32 v219, v221
	v_permlane32_swap_b32_e32 v222, v224
	v_permlane32_swap_b32_e32 v223, v225
	global_store_dwordx4 v[226:227], v[210:213], off
	global_store_dwordx4 v[226:227], v[214:217], off offset:32
	global_store_dwordx4 v[226:227], v[218:221], off offset:64
	global_store_dwordx4 v[226:227], v[222:225], off offset:96
	s_branch .LBB0_897
